# static s_setprio 1 for waves 4-7 during the attention tile loop (reset after the loop)
# speedup vs baseline: 1.0019x; 1.0019x over previous
; __device__ __forceinline__ float bflo(unsigned u) { return __uint_as_float(u << 16); }
; __device__ __forceinline__ float bfhi(unsigned u) { return __uint_as_float(u & 0xffff0000u); }
; #define DMA_WAIT_BAR() do { asm volatile("s_waitcnt vmcnt(0)" ::: "memory"); __syncthreads(); } while (0)
; #define RD_K(slot) do { const LAS unsigned char* kp_ = L + (slot) * ASLOT; \
;         _Pragma("unroll") for (int st = 0; st < 4; ++st) { kf[2 * st] = *(const LAS bf16x8*)(kp_ + (kb0 ^ (32 * st))); kf[2 * st + 1] = *(const LAS bf16x8*)(kp_ + 8192 + (kb0 ^ (32 * st))); } } while (0)
; __device__ __forceinline__ void attn_unit(LAS unsigned char* L, bf16_t* QKV, size_t rowbase, int S, int h, int qb, float lam, const float* subln, unsigned* kmax) {
;     ...
;         const int seq = rowbase < (size_t)TP ? (int)(rowbase >> 14) : 2 + (int)((rowbase - TP) >> 13);
;         unsigned* kp = kmax + (seq * 16 + 2 * h + hd) * 2;
;         const float kb = sqrtf(__uint_as_float(__hip_atomic_load(kp, __ATOMIC_RELAXED, __HIP_MEMORY_SCOPE_AGENT)) + __uint_as_float(__hip_atomic_load(kp + 1, __ATOMIC_RELAXED, __HIP_MEMORY_SCOPE_AGENT)));
;         float q2 = 0.f;
; #pragma unroll
;         for (int st = 0; st < 4; ++st) { const u32x4 w = __builtin_bit_cast(u32x4, qf[st]);
;             q2 += ((bflo(w.x) * bflo(w.x) + bfhi(w.x) * bfhi(w.x)) + (bflo(w.y) * bflo(w.y) + bfhi(w.y) * bfhi(w.y))) + ((bflo(w.z) * bflo(w.z) + bfhi(w.z) * bfhi(w.z)) + (bflo(w.w) * bflo(w.w) + bfhi(w.w) * bfhi(w.w))); }
;         q2 += __shfl_xor(q2, 32);
;         const float mref = sqrtf(q2) * kb;
; #pragma unroll
;         for (int r = 0; r < 16; ++r) negm[r] = -mref; }
;     DMA_WAIT_BAR();
;     bf16x8 kf[8], va[4], vb[4];
;     ...
;     RD_K(0);
;     __syncthreads();
.LBB0_926:
	s_lshl_b32 s5, s63, 2
	s_lshl_b32 s10, s40, 1
	s_lshl_b32 s4, s22, 5
	s_add_i32 s5, s10, s5
	s_add_i32 s10, s5, s4
	s_lshl_b32 s23, s40, 3
	s_lshl_b64 s[4:5], s[10:11], 2
	s_add_u32 s4, s26, s4
	s_addc_u32 s5, s27, s5
	global_load_dword v25, v157, s[4:5] sc1
	global_load_dword v27, v157, s[4:5] offset:4 sc1
	s_waitcnt vmcnt(5)
	v_and_b32_e32 v3, 0xffff0000, v113
	v_and_b32_e32 v2, 0xffff0000, v112
	v_and_b32_e32 v7, 0xffff0000, v115
	v_and_b32_e32 v6, 0xffff0000, v114
	s_waitcnt vmcnt(4)
	v_and_b32_e32 v11, 0xffff0000, v117
	v_and_b32_e32 v10, 0xffff0000, v116
	v_and_b32_e32 v15, 0xffff0000, v119
	v_and_b32_e32 v14, 0xffff0000, v118
	v_lshlrev_b32_e32 v1, 16, v113
	v_lshlrev_b32_e32 v0, 16, v112
	v_lshlrev_b32_e32 v5, 16, v115
	v_lshlrev_b32_e32 v4, 16, v114
	v_lshlrev_b32_e32 v9, 16, v117
	v_lshlrev_b32_e32 v8, 16, v116
	v_lshlrev_b32_e32 v13, 16, v119
	v_lshlrev_b32_e32 v12, 16, v118
	v_pk_mul_f32 v[2:3], v[2:3], v[2:3]
	v_pk_mul_f32 v[6:7], v[6:7], v[6:7]
	v_pk_mul_f32 v[10:11], v[10:11], v[10:11]
	v_pk_mul_f32 v[14:15], v[14:15], v[14:15]
	s_waitcnt vmcnt(2)
	v_lshlrev_b32_e32 v24, 16, v124
	v_and_b32_e32 v26, 0xffff0000, v124
	v_lshlrev_b32_e32 v28, 16, v125
	v_and_b32_e32 v29, 0xffff0000, v125
	v_pk_fma_f32 v[0:1], v[0:1], v[0:1], v[2:3]
	v_pk_fma_f32 v[2:3], v[4:5], v[4:5], v[6:7]
	v_pk_fma_f32 v[4:5], v[8:9], v[8:9], v[10:11]
	v_pk_fma_f32 v[6:7], v[12:13], v[12:13], v[14:15]
	v_mul_f32_e32 v35, v24, v24
	v_mul_f32_e32 v36, v26, v26
	v_mul_f32_e32 v37, v28, v28
	v_mul_f32_e32 v29, v29, v29
	v_pk_add_f32 v[0:1], v[0:1], v[0:1] op_sel:[0,1] op_sel_hi:[1,0]
	v_pk_add_f32 v[2:3], v[2:3], v[2:3] op_sel:[0,1] op_sel_hi:[1,0]
	v_pk_add_f32 v[4:5], v[4:5], v[4:5] op_sel:[0,1] op_sel_hi:[1,0]
	v_pk_add_f32 v[6:7], v[6:7], v[6:7] op_sel:[0,1] op_sel_hi:[1,0]
	v_mov_b32_e32 v1, v35
	v_mov_b32_e32 v3, v36
	v_mov_b32_e32 v5, v37
	v_mov_b32_e32 v7, v29
	v_pk_add_f32 v[0:1], v[0:1], v[2:3]
	v_pk_add_f32 v[2:3], v[4:5], v[6:7]
	v_and_b32_e32 v17, 0xffff0000, v120
	v_and_b32_e32 v19, 0xffff0000, v121
	v_and_b32_e32 v21, 0xffff0000, v122
	v_and_b32_e32 v23, 0xffff0000, v123
	v_lshlrev_b32_e32 v30, 16, v126
	v_and_b32_e32 v31, 0xffff0000, v126
	v_pk_add_f32 v[0:1], v[0:1], v[2:3]
	v_lshlrev_b32_e32 v16, 16, v120
	v_lshlrev_b32_e32 v18, 16, v121
	v_lshlrev_b32_e32 v20, 16, v122
	v_lshlrev_b32_e32 v22, 16, v123
	v_lshlrev_b32_e32 v32, 16, v127
	v_and_b32_e32 v33, 0xffff0000, v127
	v_mul_f32_e32 v38, v30, v30
	v_mul_f32_e32 v31, v31, v31
	v_mul_f32_e32 v24, v17, v17
	v_mul_f32_e32 v26, v19, v19
	v_mul_f32_e32 v28, v21, v21
	v_mul_f32_e32 v30, v23, v23
	v_mul_f32_e32 v32, v32, v32
	v_mul_f32_e32 v33, v33, v33
	v_pk_fma_f32 v[12:13], v[20:21], v[20:21], v[28:29] op_sel_hi:[1,1,0]
	v_pk_fma_f32 v[14:15], v[22:23], v[22:23], v[30:31] op_sel_hi:[1,1,0]
	v_mov_b32_e32 v13, v32
	v_mov_b32_e32 v15, v33
	v_and_b32_e32 v6, 64, v186
	v_add_u32_e32 v6, 64, v6
	v_bitop3_b32 v34, s23, v171, v181 bitop3:0x36
	v_lshl_add_u32 v34, v34, 4, v172
	v_add_u32_e32 v188, 0, v34
	s_waitcnt vmcnt(0)
	s_barrier
; __device__ __forceinline__ float bflo(unsigned u) { return __uint_as_float(u << 16); }
; __device__ __forceinline__ float bfhi(unsigned u) { return __uint_as_float(u & 0xffff0000u); }
; #define DMA_WAIT_BAR() do { asm volatile("s_waitcnt vmcnt(0)" ::: "memory"); __syncthreads(); } while (0)
; #define RD_K(slot) do { const LAS unsigned char* kp_ = L + (slot) * ASLOT; \
;         _Pragma("unroll") for (int st = 0; st < 4; ++st) { kf[2 * st] = *(const LAS bf16x8*)(kp_ + (kb0 ^ (32 * st))); kf[2 * st + 1] = *(const LAS bf16x8*)(kp_ + 8192 + (kb0 ^ (32 * st))); } } while (0)
; __device__ __forceinline__ void attn_unit(LAS unsigned char* L, bf16_t* QKV, size_t rowbase, int S, int h, int qb, float lam, const float* subln, unsigned* kmax) {
;     ...
;         const float kb = sqrtf(__uint_as_float(__hip_atomic_load(kp, __ATOMIC_RELAXED, __HIP_MEMORY_SCOPE_AGENT)) + __uint_as_float(__hip_atomic_load(kp + 1, __ATOMIC_RELAXED, __HIP_MEMORY_SCOPE_AGENT)));
;         float q2 = 0.f;
; #pragma unroll
;         for (int st = 0; st < 4; ++st) { const u32x4 w = __builtin_bit_cast(u32x4, qf[st]);
;             q2 += ((bflo(w.x) * bflo(w.x) + bfhi(w.x) * bfhi(w.x)) + (bflo(w.y) * bflo(w.y) + bfhi(w.y) * bfhi(w.y))) + ((bflo(w.z) * bflo(w.z) + bfhi(w.z) * bfhi(w.z)) + (bflo(w.w) * bflo(w.w) + bfhi(w.w) * bfhi(w.w))); }
;         q2 += __shfl_xor(q2, 32);
;         const float mref = sqrtf(q2) * kb;
; #pragma unroll
;         for (int r = 0; r < 16; ++r) negm[r] = -mref; }
;     DMA_WAIT_BAR();
;     bf16x8 kf[8], va[4], vb[4];
;     ...
;     RD_K(0);
;     __syncthreads();
;     bf16x8 pf[4];
	ds_read_b128 v[80:83], v188
	ds_read_b128 v[128:131], v188 offset:8192
	v_mov_b32_e32 v187, 0
	s_waitcnt vmcnt(1)
	v_pk_fma_f32 v[8:9], v[16:17], v[16:17], v[24:25] op_sel_hi:[1,1,0]
	s_waitcnt vmcnt(0)
	v_add_f32_e32 v2, v27, v25
	v_mul_f32_e32 v3, 0x4f800000, v2
	v_cmp_gt_f32_e32 vcc, s37, v2
	v_pk_fma_f32 v[10:11], v[18:19], v[18:19], v[26:27] op_sel_hi:[1,1,0]
	v_mov_b32_e32 v9, v38
	v_cndmask_b32_e32 v4, v2, v3, vcc
	v_mov_b32_e32 v11, v31
	v_sqrt_f32_e32 v5, v4
	v_pk_add_f32 v[8:9], v[8:9], v[10:11]
	v_pk_add_f32 v[10:11], v[12:13], v[14:15]
	s_add_i32 s24, s42, -1
	v_pk_add_f32 v[2:3], v[8:9], v[10:11]
	s_add_i32 s25, s43, 0x1c000
	v_pk_add_f32 v[0:1], v[0:1], v[2:3]
	v_xor_b32_e32 v3, 32, v186
	v_add_f32_e32 v0, v0, v1
	v_add_u32_e32 v1, -1, v5
	v_fma_f32 v2, -v1, v5, v4
	v_cmp_ge_f32_e64 s[4:5], 0, v2
	v_add_u32_e32 v2, 1, v5
	s_add_i32 s63, s43, 0x1e000
	v_cndmask_b32_e64 v1, v5, v1, s[4:5]
	v_cmp_lt_i32_e64 s[4:5], v3, v6
	v_fma_f32 v5, -v2, v5, v4
	s_mov_b32 s68, 7
	v_cndmask_b32_e64 v3, v186, v3, s[4:5]
	v_lshlrev_b32_e32 v156, 2, v3
	ds_bpermute_b32 v3, v156, v0
	v_cmp_lt_f32_e64 s[4:5], 0, v5
	v_mov_b32_e32 v192, 0
	v_mov_b32_e32 v193, 0
	v_cndmask_b32_e64 v1, v1, v2, s[4:5]
	s_waitcnt lgkmcnt(0)
	v_add_f32_e32 v0, v0, v3
	v_mul_f32_e32 v3, 0x4f800000, v0
	v_cmp_gt_f32_e64 s[4:5], s37, v0
	v_mul_f32_e32 v2, 0x37800000, v1
	v_cndmask_b32_e32 v1, v1, v2, vcc
	v_cndmask_b32_e64 v0, v0, v3, s[4:5]
	v_sqrt_f32_e32 v3, v0
	v_cmp_class_f32_e32 vcc, v4, v173
	v_mov_b32_e32 v194, 0
	v_mov_b32_e32 v5, v187
	v_add_u32_e32 v2, -1, v3
	v_cndmask_b32_e32 v1, v1, v4, vcc
	v_fma_f32 v4, -v2, v3, v0
	v_cmp_ge_f32_e32 vcc, 0, v4
	v_add_u32_e32 v4, 1, v3
	v_mov_b32_e32 v6, v187
	v_cndmask_b32_e32 v2, v3, v2, vcc
	v_fma_f32 v3, -v4, v3, v0
	v_cmp_lt_f32_e32 vcc, 0, v3
	v_mov_b32_e32 v7, v187
	v_mov_b32_e32 v8, v187
	v_cndmask_b32_e32 v2, v2, v4, vcc
	v_mul_f32_e32 v3, 0x37800000, v2
	v_cndmask_b32_e64 v2, v2, v3, s[4:5]
	v_cmp_class_f32_e32 vcc, v0, v173
	v_mov_b32_e32 v3, v187
	v_mov_b32_e32 v4, v187
	v_cndmask_b32_e32 v0, v2, v0, vcc
	v_mul_f32_e64 v64, v0, -v1
	v_xor_b32_e32 v0, 32, v34
	v_add_u32_e32 v189, 0, v0
	v_xor_b32_e32 v0, 64, v34
	v_add_u32_e32 v190, 0, v0
	v_xor_b32_e32 v0, 0x60, v34
	v_add_u32_e32 v191, 0, v0
	ds_read_b128 v[132:135], v189
	ds_read_b128 v[136:139], v189 offset:8192
	ds_read_b128 v[140:143], v190
	ds_read_b128 v[144:147], v190 offset:8192
	ds_read_b128 v[148:151], v191
	ds_read_b128 v[152:155], v191 offset:8192
	v_mov_b32_e32 v65, v64
	v_mov_b32_e32 v66, v64
	v_mov_b32_e32 v67, v64
	v_mov_b32_e32 v68, v64
	v_mov_b32_e32 v69, v64
	v_mov_b32_e32 v70, v64
	v_mov_b32_e32 v71, v64
	v_mov_b32_e32 v72, v64
	v_mov_b32_e32 v73, v64
	v_mov_b32_e32 v74, v64
	v_mov_b32_e32 v75, v64
	v_mov_b32_e32 v76, v64
	v_mov_b32_e32 v77, v64
	v_mov_b32_e32 v78, v64
	v_mov_b32_e32 v79, v64
	v_mov_b32_e32 v0, 0
	v_mov_b32_e32 v1, v187
	v_mov_b32_e32 v2, v187
	v_mov_b32_e32 v9, v187
	v_mov_b32_e32 v10, v187
	v_mov_b32_e32 v11, v187
	v_mov_b32_e32 v12, v187
	v_mov_b32_e32 v13, v187
	v_mov_b32_e32 v14, v187
	v_mov_b32_e32 v15, v187
	v_mov_b32_e32 v16, 0
	v_mov_b32_e32 v17, v187
	v_mov_b32_e32 v18, v187
	v_mov_b32_e32 v19, v187
	v_mov_b32_e32 v20, v187
	v_mov_b32_e32 v21, v187
	v_mov_b32_e32 v22, v187
	v_mov_b32_e32 v23, v187
	v_mov_b32_e32 v24, v187
	v_mov_b32_e32 v25, v187
	v_mov_b32_e32 v26, v187
	v_mov_b32_e32 v27, v187
	v_mov_b32_e32 v28, v187
	v_mov_b32_e32 v29, v187
	v_mov_b32_e32 v30, v187
	v_mov_b32_e32 v31, v187
	v_mov_b32_e32 v32, 0
	v_mov_b32_e32 v33, v187
	v_mov_b32_e32 v34, v187
	v_mov_b32_e32 v35, v187
	v_mov_b32_e32 v36, v187
	v_mov_b32_e32 v37, v187
	v_mov_b32_e32 v38, v187
	v_mov_b32_e32 v39, v187
	v_mov_b32_e32 v40, v187
	v_mov_b32_e32 v41, v187
	v_mov_b32_e32 v42, v187
	v_mov_b32_e32 v43, v187
	v_mov_b32_e32 v44, v187
	v_mov_b32_e32 v45, v187
	v_mov_b32_e32 v46, v187
	v_mov_b32_e32 v47, v187
	v_mov_b32_e32 v48, 0
	v_mov_b32_e32 v49, v187
	v_mov_b32_e32 v50, v187
	v_mov_b32_e32 v51, v187
	v_mov_b32_e32 v52, v187
	v_mov_b32_e32 v53, v187
	v_mov_b32_e32 v54, v187
	v_mov_b32_e32 v55, v187
	v_mov_b32_e32 v56, v187
	v_mov_b32_e32 v57, v187
	v_mov_b32_e32 v58, v187
	v_mov_b32_e32 v59, v187
	v_mov_b32_e32 v60, v187
	v_mov_b32_e32 v61, v187
	v_mov_b32_e32 v62, v187
	v_mov_b32_e32 v63, v187
	s_add_u32 s22, s20, 0x10000
	s_addc_u32 s23, s21, 0
	s_add_u32 s4, s20, 0x18000
	s_addc_u32 s5, s21, 0
	ds_read_b64_tr_b16 v[224:225], v174
	ds_read_b64_tr_b16 v[226:227], v175 offset:2048
	ds_read_b64_tr_b16 v[228:229], v176
	ds_read_b64_tr_b16 v[230:231], v177 offset:2048
	ds_read_b64_tr_b16 v[232:233], v178
	ds_read_b64_tr_b16 v[234:235], v179 offset:2048
	ds_read_b64_tr_b16 v[236:237], v183
	ds_read_b64_tr_b16 v[238:239], v184 offset:2048
	v_add_u32_e32 v254, 0x4000, v163
	v_add_u32_e32 v255, 0x100, v163
	v_add_u32_e32 v253, 0x4100, v163
	s_cmp_eq_u32 s40, 1
	s_cbranch_scc0 .Lattn_noprio
	s_setprio 1

.LBB0_927:
	s_add_i32 s69, s68, -3
	s_mov_b32 m0, s53
	v_mfma_f32_32x32x16_bf16 v[96:111], v[132:135], v[116:119], v[64:79]
	global_load_lds_dwordx4 v163, s[4:5]
	s_mov_b32 m0, s58
	v_mfma_f32_32x32x16_bf16 v[96:111], v[140:143], v[120:123], v[96:111]
	global_load_lds_dwordx4 v254, s[4:5]
	s_mov_b32 m0, s25
	s_waitcnt lgkmcnt(10)
	v_mfma_f32_32x32x16_bf16 v[96:111], v[148:151], v[124:127], v[96:111]
	global_load_lds_dwordx4 v255, s[4:5]
	ds_read_b64_tr_b16 v[132:133], v176 offset:4096
	ds_read_b64_tr_b16 v[134:135], v177 offset:6144
	s_mov_b32 m0, s63
	s_waitcnt lgkmcnt(10)
	v_mfma_f32_32x32x16_bf16 v[96:111], v[80:83], v[112:115], v[96:111]
	global_load_lds_dwordx4 v253, s[4:5]
	ds_read_b64_tr_b16 v[140:141], v183 offset:4096
	ds_read_b64_tr_b16 v[142:143], v184 offset:6144
	v_mfma_f32_32x32x16_bf16 v[80:95], v[128:131], v[112:115], v[64:79]
	ds_read_b64_tr_b16 v[128:129], v174 offset:4096
	ds_read_b64_tr_b16 v[130:131], v175 offset:6144
	v_mfma_f32_32x32x16_bf16 v[80:95], v[136:139], v[116:119], v[80:95]
	s_nop 3
	v_mfma_f32_32x32x16_bf16 v[80:95], v[144:147], v[120:123], v[80:95]
	v_exp_f32_e32 v96, v96
	v_exp_f32_e32 v97, v97
	v_exp_f32_e32 v98, v98
	v_mfma_f32_32x32x16_bf16 v[80:95], v[152:155], v[124:127], v[80:95]
	v_exp_f32_e32 v99, v99
	v_exp_f32_e32 v100, v100
	v_exp_f32_e32 v101, v101
	v_exp_f32_e32 v102, v102
	v_exp_f32_e32 v103, v103
	v_cvt_pk_bf16_f32 v208, v96, v97
	v_cvt_pk_bf16_f32 v209, v98, v99
	v_cvt_pk_bf16_f32 v210, v100, v101
	v_cvt_pk_bf16_f32 v211, v102, v103
	v_exp_f32_e32 v104, v104
	v_exp_f32_e32 v105, v105
	s_waitcnt lgkmcnt(6)
	v_mfma_f32_32x32x16_bf16 v[48:63], v[224:227], v[208:211], v[48:63]
	v_exp_f32_e32 v106, v106
	v_exp_f32_e32 v107, v107
	v_exp_f32_e32 v108, v108
	ds_read_b64_tr_b16 v[136:137], v178 offset:4096
	ds_read_b64_tr_b16 v[138:139], v179 offset:6144
	v_mfma_f32_32x32x16_bf16 v[32:47], v[228:231], v[208:211], v[32:47]
	v_exp_f32_e32 v109, v109
	v_exp_f32_e32 v110, v110
	v_exp_f32_e32 v111, v111
	ds_read_b64_tr_b16 v[144:145], v174 offset:8192
	ds_read_b64_tr_b16 v[146:147], v175 offset:10240
	v_mfma_f32_32x32x16_bf16 v[16:31], v[232:235], v[208:211], v[16:31]
	v_cvt_pk_bf16_f32 v212, v104, v105
	v_cvt_pk_bf16_f32 v213, v106, v107
	v_cvt_pk_bf16_f32 v214, v108, v109
	v_cvt_pk_bf16_f32 v215, v110, v111
	v_add_f32_e32 v187, v96, v187
	v_add_f32_e32 v192, v97, v192
	ds_read_b64_tr_b16 v[148:149], v176 offset:8192
	ds_read_b64_tr_b16 v[150:151], v177 offset:10240
	v_mfma_f32_32x32x16_bf16 v[0:15], v[236:239], v[208:211], v[0:15]
	v_add_f32_e32 v193, v98, v193
	v_add_f32_e32 v194, v99, v194
	v_add_f32_e32 v187, v100, v187
	v_add_f32_e32 v192, v101, v192
	v_add_f32_e32 v193, v102, v193
	v_add_f32_e32 v194, v103, v194
	ds_read_b64_tr_b16 v[152:153], v178 offset:8192
	ds_read_b64_tr_b16 v[154:155], v179 offset:10240
	s_waitcnt lgkmcnt(6)
	v_mfma_f32_32x32x16_bf16 v[48:63], v[128:131], v[212:215], v[48:63]
	v_exp_f32_e32 v80, v80
	v_exp_f32_e32 v81, v81
	v_exp_f32_e32 v82, v82
	ds_read_b64_tr_b16 v[240:241], v183 offset:8192
	ds_read_b64_tr_b16 v[242:243], v184 offset:10240
	ds_read_b128 v[128:131], v188 offset:24576
	v_mfma_f32_32x32x16_bf16 v[32:47], v[132:135], v[212:215], v[32:47]
	v_exp_f32_e32 v83, v83
	v_exp_f32_e32 v84, v84
	v_exp_f32_e32 v85, v85
	ds_read_b64_tr_b16 v[196:197], v174 offset:12288
	ds_read_b64_tr_b16 v[198:199], v175 offset:14336
	ds_read_b128 v[132:135], v189 offset:16384
	v_mfma_f32_32x32x16_bf16 v[16:31], v[136:139], v[212:215], v[16:31]
	v_exp_f32_e32 v86, v86
	v_exp_f32_e32 v87, v87
	v_cvt_pk_bf16_f32 v216, v80, v81
	v_cvt_pk_bf16_f32 v217, v82, v83
	ds_read_b64_tr_b16 v[200:201], v176 offset:12288
	ds_read_b64_tr_b16 v[202:203], v177 offset:14336
	ds_read_b128 v[136:139], v189 offset:24576
	v_mfma_f32_32x32x16_bf16 v[0:15], v[140:143], v[212:215], v[0:15]
	v_cvt_pk_bf16_f32 v218, v84, v85
	v_cvt_pk_bf16_f32 v219, v86, v87
	v_add_f32_e32 v187, v104, v187
	v_add_f32_e32 v192, v105, v192
	v_add_f32_e32 v193, v106, v193
	v_add_f32_e32 v194, v107, v194
	s_waitcnt lgkmcnt(12)
	ds_read_b64_tr_b16 v[204:205], v178 offset:12288
	ds_read_b64_tr_b16 v[206:207], v179 offset:14336
	ds_read_b128 v[140:143], v190 offset:16384
	s_waitcnt lgkmcnt(10)
	v_mfma_f32_32x32x16_bf16 v[48:63], v[144:147], v[216:219], v[48:63]
	v_exp_f32_e32 v88, v88
	v_exp_f32_e32 v89, v89
	v_exp_f32_e32 v90, v90
	ds_read_b64_tr_b16 v[246:247], v183 offset:12288
	ds_read_b64_tr_b16 v[248:249], v184 offset:14336
	ds_read_b128 v[144:147], v190 offset:24576
	v_mfma_f32_32x32x16_bf16 v[32:47], v[148:151], v[216:219], v[32:47]
	v_exp_f32_e32 v91, v91
	v_exp_f32_e32 v92, v92
	v_exp_f32_e32 v93, v93
	ds_read_b128 v[148:151], v191 offset:16384
	v_mfma_f32_32x32x16_bf16 v[16:31], v[152:155], v[216:219], v[16:31]
	v_exp_f32_e32 v94, v94
	v_exp_f32_e32 v95, v95
	v_cvt_pk_bf16_f32 v220, v88, v89
	v_cvt_pk_bf16_f32 v221, v90, v91
	ds_read_b128 v[152:155], v191 offset:24576
	v_mfma_f32_32x32x16_bf16 v[0:15], v[240:243], v[216:219], v[0:15]
	v_cvt_pk_bf16_f32 v222, v92, v93
	v_cvt_pk_bf16_f32 v223, v94, v95
	v_add_f32_e32 v187, v80, v187
	v_add_f32_e32 v192, v81, v192
	v_add_f32_e32 v193, v82, v193
	v_add_f32_e32 v194, v83, v194
	s_waitcnt lgkmcnt(3)
	v_mfma_f32_32x32x16_bf16 v[48:63], v[196:199], v[220:223], v[48:63]
	v_add_f32_e32 v187, v108, v187
	v_add_f32_e32 v192, v109, v192
	v_add_f32_e32 v193, v110, v193
	v_add_f32_e32 v194, v111, v194
	v_add_f32_e32 v187, v84, v187
	v_add_f32_e32 v192, v85, v192
	ds_read_b128 v[80:83], v188 offset:16384
	ds_read_b64_tr_b16 v[224:225], v174 offset:16384
	ds_read_b64_tr_b16 v[226:227], v175 offset:18432
	v_mfma_f32_32x32x16_bf16 v[32:47], v[200:203], v[220:223], v[32:47]
	v_add_f32_e32 v193, v86, v193
	v_add_f32_e32 v194, v87, v194
	v_add_f32_e32 v187, v88, v187
	v_add_f32_e32 v192, v89, v192
	v_add_f32_e32 v193, v90, v193
	v_add_f32_e32 v194, v91, v194
	ds_read_b64_tr_b16 v[228:229], v176 offset:16384
	ds_read_b64_tr_b16 v[230:231], v177 offset:18432
	v_mfma_f32_32x32x16_bf16 v[16:31], v[204:207], v[220:223], v[16:31]
	v_add_f32_e32 v187, v92, v187
	v_add_f32_e32 v192, v93, v192
	v_add_f32_e32 v193, v94, v193
	v_add_f32_e32 v194, v95, v194
	ds_read_b64_tr_b16 v[232:233], v178 offset:16384
	ds_read_b64_tr_b16 v[234:235], v179 offset:18432
	v_mfma_f32_32x32x16_bf16 v[0:15], v[246:249], v[220:223], v[0:15]
	ds_read_b64_tr_b16 v[236:237], v183 offset:16384
	ds_read_b64_tr_b16 v[238:239], v184 offset:18432
	s_add_i32 s10, s68, -3
	s_min_u32 s10, s10, s24
	s_lshl_b32 s10, s10, 15
	s_add_u32 s22, s20, s10
	s_addc_u32 s23, s21, 0
	s_waitcnt vmcnt(4)
	s_barrier
; __device__ __forceinline__ void attn_unit(LAS unsigned char* L, bf16_t* QKV, size_t rowbase, int S, int h, int qb, float lam, const float* subln, unsigned* kmax) {
;     ...
;     for (int t = 0; t < NT; t += 4) { TILE(t, 0); TILE(t + 1, 1); TILE(t + 2, 2); TILE(t + 3, 3); }
	s_mov_b32 m0, s43
	v_mfma_f32_32x32x16_bf16 v[96:111], v[132:135], v[116:119], v[64:79]
	global_load_lds_dwordx4 v163, s[22:23]
	s_mov_b32 m0, s45
	v_mfma_f32_32x32x16_bf16 v[96:111], v[140:143], v[120:123], v[96:111]
	global_load_lds_dwordx4 v254, s[22:23]
	s_mov_b32 m0, s44
	s_waitcnt lgkmcnt(10)
	v_mfma_f32_32x32x16_bf16 v[96:111], v[148:151], v[124:127], v[96:111]
	global_load_lds_dwordx4 v255, s[22:23]
	ds_read_b64_tr_b16 v[132:133], v176 offset:20480
	ds_read_b64_tr_b16 v[134:135], v177 offset:22528
	s_mov_b32 m0, s48
	s_waitcnt lgkmcnt(10)
	v_mfma_f32_32x32x16_bf16 v[96:111], v[80:83], v[112:115], v[96:111]
	global_load_lds_dwordx4 v253, s[22:23]
	ds_read_b64_tr_b16 v[140:141], v183 offset:20480
	ds_read_b64_tr_b16 v[142:143], v184 offset:22528
	v_mfma_f32_32x32x16_bf16 v[80:95], v[128:131], v[112:115], v[64:79]
	ds_read_b64_tr_b16 v[128:129], v174 offset:20480
	ds_read_b64_tr_b16 v[130:131], v175 offset:22528
	v_mfma_f32_32x32x16_bf16 v[80:95], v[136:139], v[116:119], v[80:95]
	s_nop 3
	v_mfma_f32_32x32x16_bf16 v[80:95], v[144:147], v[120:123], v[80:95]
	v_exp_f32_e32 v96, v96
	v_exp_f32_e32 v97, v97
	v_exp_f32_e32 v98, v98
	v_mfma_f32_32x32x16_bf16 v[80:95], v[152:155], v[124:127], v[80:95]
	v_exp_f32_e32 v99, v99
	v_exp_f32_e32 v100, v100
	v_exp_f32_e32 v101, v101
	v_exp_f32_e32 v102, v102
	v_exp_f32_e32 v103, v103
	v_cvt_pk_bf16_f32 v208, v96, v97
	v_cvt_pk_bf16_f32 v209, v98, v99
	v_cvt_pk_bf16_f32 v210, v100, v101
	v_cvt_pk_bf16_f32 v211, v102, v103
	v_exp_f32_e32 v104, v104
	v_exp_f32_e32 v105, v105
	s_waitcnt lgkmcnt(6)
	v_mfma_f32_32x32x16_bf16 v[48:63], v[224:227], v[208:211], v[48:63]
	v_exp_f32_e32 v106, v106
	v_exp_f32_e32 v107, v107
	v_exp_f32_e32 v108, v108
	ds_read_b64_tr_b16 v[136:137], v178 offset:20480
	ds_read_b64_tr_b16 v[138:139], v179 offset:22528
	v_mfma_f32_32x32x16_bf16 v[32:47], v[228:231], v[208:211], v[32:47]
	v_exp_f32_e32 v109, v109
	v_exp_f32_e32 v110, v110
	v_exp_f32_e32 v111, v111
	ds_read_b64_tr_b16 v[144:145], v174 offset:24576
	ds_read_b64_tr_b16 v[146:147], v175 offset:26624
	v_mfma_f32_32x32x16_bf16 v[16:31], v[232:235], v[208:211], v[16:31]
	v_cvt_pk_bf16_f32 v212, v104, v105
	v_cvt_pk_bf16_f32 v213, v106, v107
	v_cvt_pk_bf16_f32 v214, v108, v109
	v_cvt_pk_bf16_f32 v215, v110, v111
	v_add_f32_e32 v187, v96, v187
	v_add_f32_e32 v192, v97, v192
	ds_read_b64_tr_b16 v[148:149], v176 offset:24576
	ds_read_b64_tr_b16 v[150:151], v177 offset:26624
	v_mfma_f32_32x32x16_bf16 v[0:15], v[236:239], v[208:211], v[0:15]
	v_add_f32_e32 v193, v98, v193
	v_add_f32_e32 v194, v99, v194
	v_add_f32_e32 v187, v100, v187
	v_add_f32_e32 v192, v101, v192
	v_add_f32_e32 v193, v102, v193
	v_add_f32_e32 v194, v103, v194
	ds_read_b64_tr_b16 v[152:153], v178 offset:24576
	ds_read_b64_tr_b16 v[154:155], v179 offset:26624
	s_waitcnt lgkmcnt(6)
	v_mfma_f32_32x32x16_bf16 v[48:63], v[128:131], v[212:215], v[48:63]
	v_exp_f32_e32 v80, v80
	v_exp_f32_e32 v81, v81
	v_exp_f32_e32 v82, v82
	ds_read_b64_tr_b16 v[240:241], v183 offset:24576
	ds_read_b64_tr_b16 v[242:243], v184 offset:26624
	ds_read_b128 v[128:131], v188 offset:40960
	v_mfma_f32_32x32x16_bf16 v[32:47], v[132:135], v[212:215], v[32:47]
	v_exp_f32_e32 v83, v83
	v_exp_f32_e32 v84, v84
	v_exp_f32_e32 v85, v85
	ds_read_b64_tr_b16 v[196:197], v174 offset:28672
	ds_read_b64_tr_b16 v[198:199], v175 offset:30720
	ds_read_b128 v[132:135], v189 offset:32768
	v_mfma_f32_32x32x16_bf16 v[16:31], v[136:139], v[212:215], v[16:31]
	v_exp_f32_e32 v86, v86
	v_exp_f32_e32 v87, v87
	v_cvt_pk_bf16_f32 v216, v80, v81
	v_cvt_pk_bf16_f32 v217, v82, v83
	ds_read_b64_tr_b16 v[200:201], v176 offset:28672
	ds_read_b64_tr_b16 v[202:203], v177 offset:30720
	ds_read_b128 v[136:139], v189 offset:40960
	v_mfma_f32_32x32x16_bf16 v[0:15], v[140:143], v[212:215], v[0:15]
	v_cvt_pk_bf16_f32 v218, v84, v85
	v_cvt_pk_bf16_f32 v219, v86, v87
	v_add_f32_e32 v187, v104, v187
	v_add_f32_e32 v192, v105, v192
	v_add_f32_e32 v193, v106, v193
	v_add_f32_e32 v194, v107, v194
	s_waitcnt lgkmcnt(12)
	ds_read_b64_tr_b16 v[204:205], v178 offset:28672
	ds_read_b64_tr_b16 v[206:207], v179 offset:30720
	ds_read_b128 v[140:143], v190 offset:32768
	s_waitcnt lgkmcnt(10)
	v_mfma_f32_32x32x16_bf16 v[48:63], v[144:147], v[216:219], v[48:63]
	v_exp_f32_e32 v88, v88
	v_exp_f32_e32 v89, v89
	v_exp_f32_e32 v90, v90
	ds_read_b64_tr_b16 v[246:247], v183 offset:28672
	ds_read_b64_tr_b16 v[248:249], v184 offset:30720
	ds_read_b128 v[144:147], v190 offset:40960
	v_mfma_f32_32x32x16_bf16 v[32:47], v[148:151], v[216:219], v[32:47]
	v_exp_f32_e32 v91, v91
	v_exp_f32_e32 v92, v92
	v_exp_f32_e32 v93, v93
	ds_read_b128 v[148:151], v191 offset:32768
	v_mfma_f32_32x32x16_bf16 v[16:31], v[152:155], v[216:219], v[16:31]
	v_exp_f32_e32 v94, v94
	v_exp_f32_e32 v95, v95
	v_cvt_pk_bf16_f32 v220, v88, v89
	v_cvt_pk_bf16_f32 v221, v90, v91
	ds_read_b128 v[152:155], v191 offset:40960
	v_mfma_f32_32x32x16_bf16 v[0:15], v[240:243], v[216:219], v[0:15]
	v_cvt_pk_bf16_f32 v222, v92, v93
	v_cvt_pk_bf16_f32 v223, v94, v95
	v_add_f32_e32 v187, v80, v187
	v_add_f32_e32 v192, v81, v192
	v_add_f32_e32 v193, v82, v193
	v_add_f32_e32 v194, v83, v194
	s_waitcnt lgkmcnt(3)
	v_mfma_f32_32x32x16_bf16 v[48:63], v[196:199], v[220:223], v[48:63]
	v_add_f32_e32 v187, v108, v187
	v_add_f32_e32 v192, v109, v192
	v_add_f32_e32 v193, v110, v193
	v_add_f32_e32 v194, v111, v194
	v_add_f32_e32 v187, v84, v187
	v_add_f32_e32 v192, v85, v192
	ds_read_b128 v[80:83], v188 offset:32768
	ds_read_b64_tr_b16 v[224:225], v174 offset:32768
	ds_read_b64_tr_b16 v[226:227], v175 offset:34816
	v_mfma_f32_32x32x16_bf16 v[32:47], v[200:203], v[220:223], v[32:47]
	v_add_f32_e32 v193, v86, v193
	v_add_f32_e32 v194, v87, v194
	v_add_f32_e32 v187, v88, v187
	v_add_f32_e32 v192, v89, v192
	v_add_f32_e32 v193, v90, v193
	v_add_f32_e32 v194, v91, v194
	ds_read_b64_tr_b16 v[228:229], v176 offset:32768
	ds_read_b64_tr_b16 v[230:231], v177 offset:34816
	v_mfma_f32_32x32x16_bf16 v[16:31], v[204:207], v[220:223], v[16:31]
	v_add_f32_e32 v187, v92, v187
	v_add_f32_e32 v192, v93, v192
	v_add_f32_e32 v193, v94, v193
	v_add_f32_e32 v194, v95, v194
	ds_read_b64_tr_b16 v[232:233], v178 offset:32768
	ds_read_b64_tr_b16 v[234:235], v179 offset:34816
	v_mfma_f32_32x32x16_bf16 v[0:15], v[246:249], v[220:223], v[0:15]
	ds_read_b64_tr_b16 v[236:237], v183 offset:32768
	ds_read_b64_tr_b16 v[238:239], v184 offset:34816
	s_add_i32 s10, s68, -2
	s_min_u32 s10, s10, s24
	s_lshl_b32 s10, s10, 15
	s_add_u32 s4, s20, s10
	s_addc_u32 s5, s21, 0
	s_waitcnt vmcnt(4)
	s_barrier
; __device__ __forceinline__ void attn_unit(LAS unsigned char* L, bf16_t* QKV, size_t rowbase, int S, int h, int qb, float lam, const float* subln, unsigned* kmax) {
;     ...
;     for (int t = 0; t < NT; t += 4) { TILE(t, 0); TILE(t + 1, 1); TILE(t + 2, 2); TILE(t + 3, 3); }
	s_mov_b32 m0, s46
	v_mfma_f32_32x32x16_bf16 v[96:111], v[132:135], v[116:119], v[64:79]
	global_load_lds_dwordx4 v163, s[4:5]
	s_mov_b32 m0, s47
	v_mfma_f32_32x32x16_bf16 v[96:111], v[140:143], v[120:123], v[96:111]
	global_load_lds_dwordx4 v254, s[4:5]
	s_mov_b32 m0, s51
	s_waitcnt lgkmcnt(10)
	v_mfma_f32_32x32x16_bf16 v[96:111], v[148:151], v[124:127], v[96:111]
	global_load_lds_dwordx4 v255, s[4:5]
	ds_read_b64_tr_b16 v[132:133], v176 offset:36864
	ds_read_b64_tr_b16 v[134:135], v177 offset:38912
	s_mov_b32 m0, s52
	s_waitcnt lgkmcnt(10)
	v_mfma_f32_32x32x16_bf16 v[96:111], v[80:83], v[112:115], v[96:111]
	global_load_lds_dwordx4 v253, s[4:5]
	ds_read_b64_tr_b16 v[140:141], v183 offset:36864
	ds_read_b64_tr_b16 v[142:143], v184 offset:38912
	v_mfma_f32_32x32x16_bf16 v[80:95], v[128:131], v[112:115], v[64:79]
	ds_read_b64_tr_b16 v[128:129], v174 offset:36864
	ds_read_b64_tr_b16 v[130:131], v175 offset:38912
	v_mfma_f32_32x32x16_bf16 v[80:95], v[136:139], v[116:119], v[80:95]
	s_nop 3
	v_mfma_f32_32x32x16_bf16 v[80:95], v[144:147], v[120:123], v[80:95]
	v_exp_f32_e32 v96, v96
	v_exp_f32_e32 v97, v97
	v_exp_f32_e32 v98, v98
	v_mfma_f32_32x32x16_bf16 v[80:95], v[152:155], v[124:127], v[80:95]
	v_exp_f32_e32 v99, v99
	v_exp_f32_e32 v100, v100
	v_exp_f32_e32 v101, v101
	v_exp_f32_e32 v102, v102
	v_exp_f32_e32 v103, v103
	v_cvt_pk_bf16_f32 v208, v96, v97
	v_cvt_pk_bf16_f32 v209, v98, v99
	v_cvt_pk_bf16_f32 v210, v100, v101
	v_cvt_pk_bf16_f32 v211, v102, v103
	v_exp_f32_e32 v104, v104
	v_exp_f32_e32 v105, v105
	s_waitcnt lgkmcnt(6)
	v_mfma_f32_32x32x16_bf16 v[48:63], v[224:227], v[208:211], v[48:63]
	v_exp_f32_e32 v106, v106
	v_exp_f32_e32 v107, v107
	v_exp_f32_e32 v108, v108
	ds_read_b64_tr_b16 v[136:137], v178 offset:36864
	ds_read_b64_tr_b16 v[138:139], v179 offset:38912
	v_mfma_f32_32x32x16_bf16 v[32:47], v[228:231], v[208:211], v[32:47]
	v_exp_f32_e32 v109, v109
	v_exp_f32_e32 v110, v110
	v_exp_f32_e32 v111, v111
	ds_read_b64_tr_b16 v[144:145], v174 offset:40960
	ds_read_b64_tr_b16 v[146:147], v175 offset:43008
	v_mfma_f32_32x32x16_bf16 v[16:31], v[232:235], v[208:211], v[16:31]
	v_cvt_pk_bf16_f32 v212, v104, v105
	v_cvt_pk_bf16_f32 v213, v106, v107
	v_cvt_pk_bf16_f32 v214, v108, v109
	v_cvt_pk_bf16_f32 v215, v110, v111
	v_add_f32_e32 v187, v96, v187
	v_add_f32_e32 v192, v97, v192
	ds_read_b64_tr_b16 v[148:149], v176 offset:40960
	ds_read_b64_tr_b16 v[150:151], v177 offset:43008
	v_mfma_f32_32x32x16_bf16 v[0:15], v[236:239], v[208:211], v[0:15]
	v_add_f32_e32 v193, v98, v193
	v_add_f32_e32 v194, v99, v194
	v_add_f32_e32 v187, v100, v187
	v_add_f32_e32 v192, v101, v192
	v_add_f32_e32 v193, v102, v193
	v_add_f32_e32 v194, v103, v194
	ds_read_b64_tr_b16 v[152:153], v178 offset:40960
	ds_read_b64_tr_b16 v[154:155], v179 offset:43008
	s_waitcnt lgkmcnt(6)
	v_mfma_f32_32x32x16_bf16 v[48:63], v[128:131], v[212:215], v[48:63]
	v_exp_f32_e32 v80, v80
	v_exp_f32_e32 v81, v81
	v_exp_f32_e32 v82, v82
	ds_read_b64_tr_b16 v[240:241], v183 offset:40960
	ds_read_b64_tr_b16 v[242:243], v184 offset:43008
	ds_read_b128 v[128:131], v188 offset:57344
	v_mfma_f32_32x32x16_bf16 v[32:47], v[132:135], v[212:215], v[32:47]
	v_exp_f32_e32 v83, v83
	v_exp_f32_e32 v84, v84
	v_exp_f32_e32 v85, v85
	ds_read_b64_tr_b16 v[196:197], v174 offset:45056
	ds_read_b64_tr_b16 v[198:199], v175 offset:47104
	ds_read_b128 v[132:135], v189 offset:49152
	v_mfma_f32_32x32x16_bf16 v[16:31], v[136:139], v[212:215], v[16:31]
	v_exp_f32_e32 v86, v86
	v_exp_f32_e32 v87, v87
	v_cvt_pk_bf16_f32 v216, v80, v81
	v_cvt_pk_bf16_f32 v217, v82, v83
	ds_read_b64_tr_b16 v[200:201], v176 offset:45056
	ds_read_b64_tr_b16 v[202:203], v177 offset:47104
	ds_read_b128 v[136:139], v189 offset:57344
	v_mfma_f32_32x32x16_bf16 v[0:15], v[140:143], v[212:215], v[0:15]
	v_cvt_pk_bf16_f32 v218, v84, v85
	v_cvt_pk_bf16_f32 v219, v86, v87
	v_add_f32_e32 v187, v104, v187
	v_add_f32_e32 v192, v105, v192
	v_add_f32_e32 v193, v106, v193
	v_add_f32_e32 v194, v107, v194
	s_waitcnt lgkmcnt(12)
	ds_read_b64_tr_b16 v[204:205], v178 offset:45056
	ds_read_b64_tr_b16 v[206:207], v179 offset:47104
	ds_read_b128 v[140:143], v190 offset:49152
	s_waitcnt lgkmcnt(10)
	v_mfma_f32_32x32x16_bf16 v[48:63], v[144:147], v[216:219], v[48:63]
	v_exp_f32_e32 v88, v88
	v_exp_f32_e32 v89, v89
	v_exp_f32_e32 v90, v90
	ds_read_b64_tr_b16 v[246:247], v183 offset:45056
	ds_read_b64_tr_b16 v[248:249], v184 offset:47104
	ds_read_b128 v[144:147], v190 offset:57344
	v_mfma_f32_32x32x16_bf16 v[32:47], v[148:151], v[216:219], v[32:47]
	v_exp_f32_e32 v91, v91
	v_exp_f32_e32 v92, v92
	v_exp_f32_e32 v93, v93
	ds_read_b128 v[148:151], v191 offset:49152
	v_mfma_f32_32x32x16_bf16 v[16:31], v[152:155], v[216:219], v[16:31]
	v_exp_f32_e32 v94, v94
	v_exp_f32_e32 v95, v95
	v_cvt_pk_bf16_f32 v220, v88, v89
	v_cvt_pk_bf16_f32 v221, v90, v91
	ds_read_b128 v[152:155], v191 offset:57344
	v_mfma_f32_32x32x16_bf16 v[0:15], v[240:243], v[216:219], v[0:15]
	v_cvt_pk_bf16_f32 v222, v92, v93
	v_cvt_pk_bf16_f32 v223, v94, v95
	v_add_f32_e32 v187, v80, v187
	v_add_f32_e32 v192, v81, v192
	v_add_f32_e32 v193, v82, v193
	v_add_f32_e32 v194, v83, v194
	s_waitcnt lgkmcnt(3)
	v_mfma_f32_32x32x16_bf16 v[48:63], v[196:199], v[220:223], v[48:63]
	v_add_f32_e32 v187, v108, v187
	v_add_f32_e32 v192, v109, v192
	v_add_f32_e32 v193, v110, v193
	v_add_f32_e32 v194, v111, v194
	v_add_f32_e32 v187, v84, v187
	v_add_f32_e32 v192, v85, v192
	ds_read_b128 v[80:83], v188 offset:49152
	ds_read_b64_tr_b16 v[224:225], v174 offset:49152
	ds_read_b64_tr_b16 v[226:227], v175 offset:51200
	v_mfma_f32_32x32x16_bf16 v[32:47], v[200:203], v[220:223], v[32:47]
	v_add_f32_e32 v193, v86, v193
	v_add_f32_e32 v194, v87, v194
	v_add_f32_e32 v187, v88, v187
	v_add_f32_e32 v192, v89, v192
	v_add_f32_e32 v193, v90, v193
	v_add_f32_e32 v194, v91, v194
	ds_read_b64_tr_b16 v[228:229], v176 offset:49152
	ds_read_b64_tr_b16 v[230:231], v177 offset:51200
	v_mfma_f32_32x32x16_bf16 v[16:31], v[204:207], v[220:223], v[16:31]
	v_add_f32_e32 v187, v92, v187
	v_add_f32_e32 v192, v93, v192
	v_add_f32_e32 v193, v94, v193
	v_add_f32_e32 v194, v95, v194
	ds_read_b64_tr_b16 v[232:233], v178 offset:49152
	ds_read_b64_tr_b16 v[234:235], v179 offset:51200
	v_mfma_f32_32x32x16_bf16 v[0:15], v[246:249], v[220:223], v[0:15]
	ds_read_b64_tr_b16 v[236:237], v183 offset:49152
	ds_read_b64_tr_b16 v[238:239], v184 offset:51200
	s_add_i32 s10, s68, -1
	s_min_u32 s10, s10, s24
	s_lshl_b32 s10, s10, 15
	s_add_u32 s22, s20, s10
	s_addc_u32 s23, s21, 0
	s_waitcnt vmcnt(4)
	s_barrier
; __device__ __forceinline__ void attn_unit(LAS unsigned char* L, bf16_t* QKV, size_t rowbase, int S, int h, int qb, float lam, const float* subln, unsigned* kmax) {
;     ...
;     for (int t = 0; t < NT; t += 4) { TILE(t, 0); TILE(t + 1, 1); TILE(t + 2, 2); TILE(t + 3, 3); }
	s_mov_b32 m0, s49
	v_mfma_f32_32x32x16_bf16 v[96:111], v[132:135], v[116:119], v[64:79]
	global_load_lds_dwordx4 v163, s[22:23]
	s_mov_b32 m0, s50
	v_mfma_f32_32x32x16_bf16 v[96:111], v[140:143], v[120:123], v[96:111]
	global_load_lds_dwordx4 v254, s[22:23]
	s_mov_b32 m0, s59
	s_waitcnt lgkmcnt(10)
	v_mfma_f32_32x32x16_bf16 v[96:111], v[148:151], v[124:127], v[96:111]
	global_load_lds_dwordx4 v255, s[22:23]
	ds_read_b64_tr_b16 v[132:133], v176 offset:53248
	ds_read_b64_tr_b16 v[134:135], v177 offset:55296
	s_mov_b32 m0, s61
	s_waitcnt lgkmcnt(10)
	v_mfma_f32_32x32x16_bf16 v[96:111], v[80:83], v[112:115], v[96:111]
	global_load_lds_dwordx4 v253, s[22:23]
	ds_read_b64_tr_b16 v[140:141], v183 offset:53248
	ds_read_b64_tr_b16 v[142:143], v184 offset:55296
	v_mfma_f32_32x32x16_bf16 v[80:95], v[128:131], v[112:115], v[64:79]
	ds_read_b64_tr_b16 v[128:129], v174 offset:53248
	ds_read_b64_tr_b16 v[130:131], v175 offset:55296
	v_mfma_f32_32x32x16_bf16 v[80:95], v[136:139], v[116:119], v[80:95]
	s_nop 3
	v_mfma_f32_32x32x16_bf16 v[80:95], v[144:147], v[120:123], v[80:95]
	v_exp_f32_e32 v96, v96
	v_exp_f32_e32 v97, v97
	v_exp_f32_e32 v98, v98
	v_mfma_f32_32x32x16_bf16 v[80:95], v[152:155], v[124:127], v[80:95]
	v_exp_f32_e32 v99, v99
	v_exp_f32_e32 v100, v100
	v_exp_f32_e32 v101, v101
	v_exp_f32_e32 v102, v102
	v_exp_f32_e32 v103, v103
	v_cvt_pk_bf16_f32 v208, v96, v97
	v_cvt_pk_bf16_f32 v209, v98, v99
	v_cvt_pk_bf16_f32 v210, v100, v101
	v_cvt_pk_bf16_f32 v211, v102, v103
	v_exp_f32_e32 v104, v104
	v_exp_f32_e32 v105, v105
	s_waitcnt lgkmcnt(6)
	v_mfma_f32_32x32x16_bf16 v[48:63], v[224:227], v[208:211], v[48:63]
	v_exp_f32_e32 v106, v106
	v_exp_f32_e32 v107, v107
	v_exp_f32_e32 v108, v108
	ds_read_b64_tr_b16 v[136:137], v178 offset:53248
	ds_read_b64_tr_b16 v[138:139], v179 offset:55296
	v_mfma_f32_32x32x16_bf16 v[32:47], v[228:231], v[208:211], v[32:47]
	v_exp_f32_e32 v109, v109
	v_exp_f32_e32 v110, v110
	v_exp_f32_e32 v111, v111
	ds_read_b64_tr_b16 v[144:145], v174 offset:57344
	ds_read_b64_tr_b16 v[146:147], v175 offset:59392
	v_mfma_f32_32x32x16_bf16 v[16:31], v[232:235], v[208:211], v[16:31]
	v_cvt_pk_bf16_f32 v212, v104, v105
	v_cvt_pk_bf16_f32 v213, v106, v107
	v_cvt_pk_bf16_f32 v214, v108, v109
	v_cvt_pk_bf16_f32 v215, v110, v111
	v_add_f32_e32 v187, v96, v187
	v_add_f32_e32 v192, v97, v192
	ds_read_b64_tr_b16 v[148:149], v176 offset:57344
	ds_read_b64_tr_b16 v[150:151], v177 offset:59392
	v_mfma_f32_32x32x16_bf16 v[0:15], v[236:239], v[208:211], v[0:15]
	v_add_f32_e32 v193, v98, v193
	v_add_f32_e32 v194, v99, v194
	v_add_f32_e32 v187, v100, v187
	v_add_f32_e32 v192, v101, v192
	v_add_f32_e32 v193, v102, v193
	v_add_f32_e32 v194, v103, v194
	ds_read_b64_tr_b16 v[152:153], v178 offset:57344
	ds_read_b64_tr_b16 v[154:155], v179 offset:59392
	s_waitcnt lgkmcnt(6)
	v_mfma_f32_32x32x16_bf16 v[48:63], v[128:131], v[212:215], v[48:63]
	v_exp_f32_e32 v80, v80
	v_exp_f32_e32 v81, v81
	v_exp_f32_e32 v82, v82
	ds_read_b64_tr_b16 v[240:241], v183 offset:57344
	ds_read_b64_tr_b16 v[242:243], v184 offset:59392
	ds_read_b128 v[128:131], v188 offset:8192
	v_mfma_f32_32x32x16_bf16 v[32:47], v[132:135], v[212:215], v[32:47]
	v_exp_f32_e32 v83, v83
	v_exp_f32_e32 v84, v84
	v_exp_f32_e32 v85, v85
	ds_read_b64_tr_b16 v[196:197], v174 offset:61440
	ds_read_b64_tr_b16 v[198:199], v175 offset:63488
	ds_read_b128 v[132:135], v189
	v_mfma_f32_32x32x16_bf16 v[16:31], v[136:139], v[212:215], v[16:31]
	v_exp_f32_e32 v86, v86
	v_exp_f32_e32 v87, v87
	v_cvt_pk_bf16_f32 v216, v80, v81
	v_cvt_pk_bf16_f32 v217, v82, v83
	ds_read_b64_tr_b16 v[200:201], v176 offset:61440
	ds_read_b64_tr_b16 v[202:203], v177 offset:63488
	ds_read_b128 v[136:139], v189 offset:8192
	v_mfma_f32_32x32x16_bf16 v[0:15], v[140:143], v[212:215], v[0:15]
	v_cvt_pk_bf16_f32 v218, v84, v85
	v_cvt_pk_bf16_f32 v219, v86, v87
	v_add_f32_e32 v187, v104, v187
	v_add_f32_e32 v192, v105, v192
	v_add_f32_e32 v193, v106, v193
	v_add_f32_e32 v194, v107, v194
	s_waitcnt lgkmcnt(12)
	ds_read_b64_tr_b16 v[204:205], v178 offset:61440
	ds_read_b64_tr_b16 v[206:207], v179 offset:63488
	ds_read_b128 v[140:143], v190
	s_waitcnt lgkmcnt(10)
	v_mfma_f32_32x32x16_bf16 v[48:63], v[144:147], v[216:219], v[48:63]
	v_exp_f32_e32 v88, v88
	v_exp_f32_e32 v89, v89
	v_exp_f32_e32 v90, v90
	ds_read_b64_tr_b16 v[246:247], v183 offset:61440
	ds_read_b64_tr_b16 v[248:249], v184 offset:63488
	ds_read_b128 v[144:147], v190 offset:8192
	v_mfma_f32_32x32x16_bf16 v[32:47], v[148:151], v[216:219], v[32:47]
	v_exp_f32_e32 v91, v91
	v_exp_f32_e32 v92, v92
	v_exp_f32_e32 v93, v93
	ds_read_b128 v[148:151], v191
	v_mfma_f32_32x32x16_bf16 v[16:31], v[152:155], v[216:219], v[16:31]
	v_exp_f32_e32 v94, v94
	v_exp_f32_e32 v95, v95
	v_cvt_pk_bf16_f32 v220, v88, v89
	v_cvt_pk_bf16_f32 v221, v90, v91
	ds_read_b128 v[152:155], v191 offset:8192
	v_mfma_f32_32x32x16_bf16 v[0:15], v[240:243], v[216:219], v[0:15]
	v_cvt_pk_bf16_f32 v222, v92, v93
	v_cvt_pk_bf16_f32 v223, v94, v95
	v_add_f32_e32 v187, v80, v187
	v_add_f32_e32 v192, v81, v192
	v_add_f32_e32 v193, v82, v193
	v_add_f32_e32 v194, v83, v194
	s_waitcnt lgkmcnt(3)
	v_mfma_f32_32x32x16_bf16 v[48:63], v[196:199], v[220:223], v[48:63]
	v_add_f32_e32 v187, v108, v187
	v_add_f32_e32 v192, v109, v192
	v_add_f32_e32 v193, v110, v193
	v_add_f32_e32 v194, v111, v194
	v_add_f32_e32 v187, v84, v187
	v_add_f32_e32 v192, v85, v192
	ds_read_b128 v[80:83], v188
	ds_read_b64_tr_b16 v[224:225], v174
	ds_read_b64_tr_b16 v[226:227], v175 offset:2048
	v_mfma_f32_32x32x16_bf16 v[32:47], v[200:203], v[220:223], v[32:47]
	v_add_f32_e32 v193, v86, v193
	v_add_f32_e32 v194, v87, v194
	v_add_f32_e32 v187, v88, v187
	v_add_f32_e32 v192, v89, v192
	v_add_f32_e32 v193, v90, v193
	v_add_f32_e32 v194, v91, v194
	ds_read_b64_tr_b16 v[228:229], v176
	ds_read_b64_tr_b16 v[230:231], v177 offset:2048
	v_mfma_f32_32x32x16_bf16 v[16:31], v[204:207], v[220:223], v[16:31]
	v_add_f32_e32 v187, v92, v187
	v_add_f32_e32 v192, v93, v192
	v_add_f32_e32 v193, v94, v193
	v_add_f32_e32 v194, v95, v194
	ds_read_b64_tr_b16 v[232:233], v178
	ds_read_b64_tr_b16 v[234:235], v179 offset:2048
	v_mfma_f32_32x32x16_bf16 v[0:15], v[246:249], v[220:223], v[0:15]
	ds_read_b64_tr_b16 v[236:237], v183
	ds_read_b64_tr_b16 v[238:239], v184 offset:2048
	s_min_u32 s10, s68, s24
	s_lshl_b32 s10, s10, 15
	s_add_u32 s4, s20, s10
	s_addc_u32 s5, s21, 0
	s_waitcnt vmcnt(4)
	s_add_i32 s68, s68, 4
	s_cmp_ge_u32 s69, s42
	s_barrier
; #define LAS __attribute__((address_space(3)))
; #define DMA_WAIT_BAR() do { asm volatile("s_waitcnt vmcnt(0)" ::: "memory"); __syncthreads(); } while (0)
; __device__ __forceinline__ void attn_unit(LAS unsigned char* L, bf16_t* QKV, size_t rowbase, int S, int h, int qb, float lam, const float* subln, unsigned* kmax) {
;     ...
;     for (int t = 0; t < NT; t += 4) { TILE(t, 0); TILE(t + 1, 1); TILE(t + 2, 2); TILE(t + 3, 3); }
;     ...
;     DMA_WAIT_BAR();
;     ...
;     lsum = (lsum + lsb) + (lsc + lsd);
;     const float inv = 1.f / (lsum + __shfl_xor(lsum, 32));
;     LAS float* X = (LAS float*)L;
;     const int xo = (32 * qblk + r32) * AXP + 4 * hi;
;     if (hd == 1) { const float sc = inv * lam;
; #pragma unroll
;         for (int d = 0; d < 4; ++d)
; #pragma unroll
;             for (int rg = 0; rg < 4; ++rg) *(LAS f32x4*)(X + xo + 32 * d + 8 * rg) = (f32x4){o[d][4 * rg] * sc, o[d][4 * rg + 1] * sc, o[d][4 * rg + 2] * sc, o[d][4 * rg + 3] * sc}; }
	s_cbranch_scc0 .LBB0_927
	s_setprio 0
	v_add_f32_e32 v64, v187, v192
	v_add_f32_e32 v65, v193, v194
	v_add_f32_e32 v64, v64, v65
	ds_bpermute_b32 v65, v156, v64
	s_waitcnt vmcnt(0)
	s_cmp_eq_u32 s40, 1
	s_waitcnt lgkmcnt(0)
	s_barrier
	v_add_f32_e32 v64, v64, v65
	v_div_scale_f32 v65, s[4:5], v64, v64, 1.0
	v_rcp_f32_e32 v66, v65
	s_nop 0
	v_fma_f32 v67, -v65, v66, 1.0
	v_fmac_f32_e32 v66, v67, v66
	v_div_scale_f32 v67, vcc, 1.0, v64, 1.0
	v_mul_f32_e32 v68, v67, v66
	v_fma_f32 v69, -v65, v68, v67
	v_fmac_f32_e32 v68, v69, v66
	v_fma_f32 v65, -v65, v68, v67
	v_div_fmas_f32 v65, v65, v66, v68
	v_div_fixup_f32 v66, v65, v64, 1.0
	v_or_b32_e32 v64, s41, v182
	v_mad_u32_u24 v64, v64, s38, v158
	v_lshl_add_u32 v64, v64, 2, 0
	s_cbranch_scc0 .LBB0_930
	v_mul_f32_e32 v72, v159, v66
	v_pk_mul_f32 v[68:69], v[48:49], v[72:73] op_sel_hi:[1,0]
	v_pk_mul_f32 v[70:71], v[50:51], v[72:73] op_sel_hi:[1,0]
	ds_write_b128 v64, v[68:71]
	v_pk_mul_f32 v[68:69], v[52:53], v[72:73] op_sel_hi:[1,0]
	v_pk_mul_f32 v[70:71], v[54:55], v[72:73] op_sel_hi:[1,0]
	ds_write_b128 v64, v[68:71] offset:32
	v_pk_mul_f32 v[68:69], v[56:57], v[72:73] op_sel_hi:[1,0]
	v_pk_mul_f32 v[70:71], v[58:59], v[72:73] op_sel_hi:[1,0]
	ds_write_b128 v64, v[68:71] offset:64
	v_pk_mul_f32 v[68:69], v[60:61], v[72:73] op_sel_hi:[1,0]
	v_pk_mul_f32 v[70:71], v[62:63], v[72:73] op_sel_hi:[1,0]
	ds_write_b128 v64, v[68:71] offset:96
	v_pk_mul_f32 v[68:69], v[32:33], v[72:73] op_sel_hi:[1,0]
	v_pk_mul_f32 v[70:71], v[34:35], v[72:73] op_sel_hi:[1,0]
	ds_write_b128 v64, v[68:71] offset:128
	v_pk_mul_f32 v[68:69], v[36:37], v[72:73] op_sel_hi:[1,0]
	v_pk_mul_f32 v[70:71], v[38:39], v[72:73] op_sel_hi:[1,0]
	ds_write_b128 v64, v[68:71] offset:160
	v_pk_mul_f32 v[68:69], v[40:41], v[72:73] op_sel_hi:[1,0]
	v_pk_mul_f32 v[70:71], v[42:43], v[72:73] op_sel_hi:[1,0]
	ds_write_b128 v64, v[68:71] offset:192
	v_pk_mul_f32 v[68:69], v[44:45], v[72:73] op_sel_hi:[1,0]
	v_pk_mul_f32 v[70:71], v[46:47], v[72:73] op_sel_hi:[1,0]
	ds_write_b128 v64, v[68:71] offset:224
	v_pk_mul_f32 v[68:69], v[16:17], v[72:73] op_sel_hi:[1,0]
	v_pk_mul_f32 v[70:71], v[18:19], v[72:73] op_sel_hi:[1,0]
	ds_write_b128 v64, v[68:71] offset:256
	v_pk_mul_f32 v[68:69], v[20:21], v[72:73] op_sel_hi:[1,0]
	v_pk_mul_f32 v[70:71], v[22:23], v[72:73] op_sel_hi:[1,0]
	ds_write_b128 v64, v[68:71] offset:288
	v_pk_mul_f32 v[68:69], v[24:25], v[72:73] op_sel_hi:[1,0]
	v_pk_mul_f32 v[70:71], v[26:27], v[72:73] op_sel_hi:[1,0]
	ds_write_b128 v64, v[68:71] offset:320
	v_pk_mul_f32 v[68:69], v[28:29], v[72:73] op_sel_hi:[1,0]
	v_pk_mul_f32 v[70:71], v[30:31], v[72:73] op_sel_hi:[1,0]
	ds_write_b128 v64, v[68:71] offset:352
	v_pk_mul_f32 v[68:69], v[0:1], v[72:73] op_sel_hi:[1,0]
	v_pk_mul_f32 v[70:71], v[2:3], v[72:73] op_sel_hi:[1,0]
	ds_write_b128 v64, v[68:71] offset:384
	v_pk_mul_f32 v[68:69], v[4:5], v[72:73] op_sel_hi:[1,0]
	v_pk_mul_f32 v[70:71], v[6:7], v[72:73] op_sel_hi:[1,0]
	ds_write_b128 v64, v[68:71] offset:416
	v_pk_mul_f32 v[68:69], v[8:9], v[72:73] op_sel_hi:[1,0]
	v_pk_mul_f32 v[70:71], v[10:11], v[72:73] op_sel_hi:[1,0]
	ds_write_b128 v64, v[68:71] offset:448
	v_pk_mul_f32 v[68:69], v[12:13], v[72:73] op_sel_hi:[1,0]
	v_pk_mul_f32 v[70:71], v[14:15], v[72:73] op_sel_hi:[1,0]
	ds_write_b128 v64, v[68:71] offset:480
